# UP: removed two store-drain vmcnt(0) waits (epilogue item 2, unit-loop top)
# baseline (speedup 1.0000x reference)
; template <int EPI> ...
;     ...
;         const char* nA = has_next ? (const char*)((EPI == EPI_GLU && nxt_src) ? gA2 : gA) + (size_t)nxt_pm * tstep + (size_t)nxt_k0 * kstep : cA;
;         const char* nB = has_next ? (const char*)((EPI == EPI_GLU && nxt_src) ? gBt2 : gBt) + (size_t)nxt_pn * tstep + (size_t)nxt_k0 * kstep : cB;
;         const int cnk = cur_nk;
;         for (int t = 0; t < cnk; t += 2) {
;             const bool last = (t == cnk - 2);
;             const char* a1 = cA + (size_t)(t + 1) * kstep;
;             const char* a2 = last ? nA : cA + (size_t)(t + 2) * kstep; const char* b2 = last ? nB : cB + (size_t)(t + 2) * kstep;
;             const char* a3 = a2 + kstep; const char* b3 = b2 + kstep;
;     ...
;         for (int a = 0; a < 2; ++a)
; #pragma unroll
;             for (int b = 0; b < 2; ++b)
; #pragma unroll
;                 for (int m = 0; m < 4; ++m)
; #pragma unroll
;                     for (int n = 0; n < 2; ++n) acc[a][b][m][n] = (f32x4){0.f, 0.f, 0.f, 0.f};
;         cur_pm = nxt_pm; cur_pn = nxt_pn; cur_k0 = nxt_k0; cur_nk = nxt_nk; cur_slice = nxt_slice; cur_src = nxt_src; cA = nA; cB = nB; ++ui;
.LBB0_969:
	s_ashr_i32 s49, s48, 31
	s_lshl_b64 s[50:51], s[48:49], 19
	s_add_u32 s50, s20, s50
	s_addc_u32 s51, s21, s51
	s_and_b64 s[52:53], s[16:17], exec
	s_cselect_b32 s19, s51, s57
	s_cselect_b32 s49, s50, s56
	s_ashr_i32 s47, s46, 31
	s_lshl_b64 s[52:53], s[46:47], 19
	s_add_u32 s52, s3, s52
	s_addc_u32 s53, s64, s53
	s_and_b64 s[60:61], s[16:17], exec
	s_cselect_b32 s47, s53, s59
	s_cselect_b32 s55, s52, s58
	s_add_u32 s56, s56, 0x40080
	s_addc_u32 s57, s57, 0
	s_add_u32 s62, s58, 0x100
	v_mov_b32_e32 v2, 0
	s_addc_u32 s63, s59, 0
	s_mov_b32 s83, -2
	v_mov_b32_e32 v3, v2
	v_mov_b32_e32 v4, v2
	v_mov_b32_e32 v5, v2
	v_mov_b32_e32 v6, v2
	v_mov_b32_e32 v7, v2
	v_mov_b32_e32 v8, v2
	v_mov_b32_e32 v9, v2
	v_mov_b32_e32 v26, v2
	v_mov_b32_e32 v27, v2
	v_mov_b32_e32 v28, v2
	v_mov_b32_e32 v29, v2
	v_mov_b32_e32 v18, v2
	v_mov_b32_e32 v19, v2
	v_mov_b32_e32 v20, v2
	v_mov_b32_e32 v21, v2
	v_mov_b32_e32 v74, v2
	v_mov_b32_e32 v75, v2
	v_mov_b32_e32 v76, v2
	v_mov_b32_e32 v77, v2
	v_mov_b32_e32 v34, v2
	v_mov_b32_e32 v35, v2
	v_mov_b32_e32 v36, v2
	v_mov_b32_e32 v37, v2
	v_mov_b32_e32 v90, v2
	v_mov_b32_e32 v91, v2
	v_mov_b32_e32 v92, v2
	v_mov_b32_e32 v93, v2
	v_mov_b32_e32 v82, v2
	v_mov_b32_e32 v83, v2
	v_mov_b32_e32 v84, v2
	v_mov_b32_e32 v85, v2
	v_mov_b32_e32 v10, v2
	v_mov_b32_e32 v11, v2
	v_mov_b32_e32 v12, v2
	v_mov_b32_e32 v13, v2
	v_mov_b32_e32 v14, v2
	v_mov_b32_e32 v15, v2
	v_mov_b32_e32 v16, v2
	v_mov_b32_e32 v17, v2
	v_mov_b32_e32 v30, v2
	v_mov_b32_e32 v31, v2
	v_mov_b32_e32 v32, v2
	v_mov_b32_e32 v33, v2
	v_mov_b32_e32 v22, v2
	v_mov_b32_e32 v23, v2
	v_mov_b32_e32 v24, v2
	v_mov_b32_e32 v25, v2
	v_mov_b32_e32 v78, v2
	v_mov_b32_e32 v79, v2
	v_mov_b32_e32 v80, v2
	v_mov_b32_e32 v81, v2
	v_mov_b32_e32 v62, v2
	v_mov_b32_e32 v63, v2
	v_mov_b32_e32 v64, v2
	v_mov_b32_e32 v65, v2
	v_mov_b32_e32 v94, v2
	v_mov_b32_e32 v95, v2
	v_mov_b32_e32 v96, v2
	v_mov_b32_e32 v97, v2
	v_mov_b32_e32 v86, v2
	v_mov_b32_e32 v87, v2
	v_mov_b32_e32 v88, v2
	v_mov_b32_e32 v89, v2
	v_mov_b32_e32 v98, v2
	v_mov_b32_e32 v99, v2
	v_mov_b32_e32 v100, v2
	v_mov_b32_e32 v101, v2
	v_mov_b32_e32 v102, v2
	v_mov_b32_e32 v103, v2
	v_mov_b32_e32 v104, v2
	v_mov_b32_e32 v105, v2
	v_mov_b32_e32 v122, v2
	v_mov_b32_e32 v123, v2
	v_mov_b32_e32 v124, v2
	v_mov_b32_e32 v125, v2
	v_mov_b32_e32 v114, v2
	v_mov_b32_e32 v115, v2
	v_mov_b32_e32 v116, v2
	v_mov_b32_e32 v117, v2
	v_mov_b32_e32 v138, v2
	v_mov_b32_e32 v139, v2
	v_mov_b32_e32 v140, v2
	v_mov_b32_e32 v141, v2
	v_mov_b32_e32 v130, v2
	v_mov_b32_e32 v131, v2
	v_mov_b32_e32 v132, v2
	v_mov_b32_e32 v133, v2
	v_mov_b32_e32 v154, v2
	v_mov_b32_e32 v155, v2
	v_mov_b32_e32 v156, v2
	v_mov_b32_e32 v157, v2
	v_mov_b32_e32 v146, v2
	v_mov_b32_e32 v147, v2
	v_mov_b32_e32 v148, v2
	v_mov_b32_e32 v149, v2
	v_mov_b32_e32 v106, v2
	v_mov_b32_e32 v107, v2
	v_mov_b32_e32 v108, v2
	v_mov_b32_e32 v109, v2
	v_mov_b32_e32 v110, v2
	v_mov_b32_e32 v111, v2
	v_mov_b32_e32 v112, v2
	v_mov_b32_e32 v113, v2
	v_mov_b32_e32 v126, v2
	v_mov_b32_e32 v127, v2
	v_mov_b32_e32 v128, v2
	v_mov_b32_e32 v129, v2
	v_mov_b32_e32 v118, v2
	v_mov_b32_e32 v119, v2
	v_mov_b32_e32 v120, v2
	v_mov_b32_e32 v121, v2
	v_mov_b32_e32 v142, v2
	v_mov_b32_e32 v143, v2
	v_mov_b32_e32 v144, v2
	v_mov_b32_e32 v145, v2
	v_mov_b32_e32 v134, v2
	v_mov_b32_e32 v135, v2
	v_mov_b32_e32 v136, v2
	v_mov_b32_e32 v137, v2
	v_mov_b32_e32 v158, v2
	v_mov_b32_e32 v159, v2
	v_mov_b32_e32 v160, v2
	v_mov_b32_e32 v161, v2
	v_mov_b32_e32 v150, v2
	v_mov_b32_e32 v151, v2
	v_mov_b32_e32 v152, v2
	v_mov_b32_e32 v153, v2

; __device__ __forceinline__ float gelu_tanh(float x) { float z = 1.5957691216057308f * (x + 0.044715f * x * x * x); return x * rcp_nr(1.f + __expf(fminf(-z, 80.f))); }
; __device__ __forceinline__ u32x2 pk4(f32x4 v) { u32x2 r; r.x = pk2(v.x, v.y); r.y = pk2(v.z, v.w); return r; }
; __device__ __forceinline__ f32x4 ror1v(f32x4 v) { return f32x4{dpp_ror1(v.x), dpp_ror1(v.y), dpp_ror1(v.z), dpp_ror1(v.w)}; }
; __device__ __forceinline__ f32x4 ror2v(f32x4 v) { return f32x4{dpp_ror2(v.x), dpp_ror2(v.y), dpp_ror2(v.z), dpp_ror2(v.w)}; }
; template <int EPI>
; __device__ __forceinline__ void epilogue(const Params& p, f32x4 (&acc)[2][2][4][2], const int pm, const int pn, const int wr, const int wc, const int fr, const int fq) {
;     ...
;             const int pos = row & 2047;
;             if (pos >= 2046) *(f32x4*)(p.out + O_CP + ((size_t)(row >> 11) * 2 + (pos - 2046)) * DFF + j0) = a0;
;           } else {
;             const int sidx = row - MP, b = sidx >> 2, tt = sidx & 3;
;             const f32x4 st0 = *(const f32x4*)(p.in[6] + ((size_t)b * 2 + 0) * DFF + j0);
;             const f32x4 st1 = *(const f32x4*)(p.in[6] + ((size_t)b * 2 + 1) * DFF + j0);
;             const f32x4 s1 = ror1v(a0), s2 = ror2v(a0);
;             am1 = (tt >= 1) ? s1 : st1;
;             am2 = (tt >= 2) ? s2 : ((tt == 1) ? st1 : st0);
;             if (tt >= 2) *(f32x4*)(p.out + O_CS + ((size_t)b * 2 + (tt - 2)) * DFF + j0) = a0;
;           }
;           f32x4 h;
;           h.x = gelu_tanh(cb[bj].x + w0[bj].x * am2.x + w1[bj].x * am1.x + w2[bj].x * a0.x) * g.x;
;           h.y = gelu_tanh(cb[bj].y + w0[bj].y * am2.y + w1[bj].y * am1.y + w2[bj].y * a0.y) * g.y;
;           h.z = gelu_tanh(cb[bj].z + w0[bj].z * am2.z + w1[bj].z * am1.z + w2[bj].z * a0.z) * g.z;
;           h.w = gelu_tanh(cb[bj].w + w0[bj].w * am2.w + w1[bj].w * am1.w + w2[bj].w * a0.w) * g.w;
;           ho[bj] = pk4(h);
;           if (defer) {
;             *(f32x4*)(HA0 + ((size_t)(rblk >> 6) * 2 + fr) * DFF + j0) = a0;
;             *(f32x4*)(HG0 + ((size_t)(rblk >> 6) * 2 + fr) * DFF + j0) = g;
;           }
;         }
;         if (!defer) *(u32x4*)(H + (size_t)row * DFF + jb) = u32x4{ho[0].x, ho[0].y, ho[1].x, ho[1].y};
.LBB0_1003:
	v_pk_fma_f32 v[146:147], v[54:55], v[154:155], v[70:71]
	v_pk_fma_f32 v[154:155], v[56:57], v[156:157], v[72:73]
	v_pk_fma_f32 v[146:147], v[58:59], v[158:159], v[146:147]
	v_pk_fma_f32 v[154:155], v[60:61], v[160:161], v[154:155]
	v_pk_fma_f32 v[146:147], v[134:135], v[66:67], v[146:147]
	v_pk_fma_f32 v[154:155], v[136:137], v[68:69], v[154:155]
	v_mul_f32_e32 v148, 0x3d372713, v146
	v_mul_f32_e32 v149, 0x3d372713, v147
	v_mul_f32_e32 v148, v146, v148
	v_mul_f32_e32 v149, v147, v149
	v_fma_f32 v148, v146, v148, v146
	v_fma_f32 v149, v147, v149, v147
	v_mul_f32_e32 v148, 0xbfcc422a, v148
	v_mul_f32_e32 v149, 0xbfcc422a, v149
	v_mul_f32_e32 v158, 0x3d372713, v154
	v_mul_f32_e32 v159, 0x3d372713, v155
	v_min_f32_e32 v148, 0x42a00000, v148
	v_min_f32_e32 v149, 0x42a00000, v149
	v_mul_f32_e32 v158, v154, v158
	v_mul_f32_e32 v159, v155, v159
	v_mul_f32_e32 v148, 0x3fb8aa3b, v148
	v_mul_f32_e32 v149, 0x3fb8aa3b, v149
	v_fma_f32 v158, v154, v158, v154
	v_fma_f32 v159, v155, v159, v155
	v_exp_f32_e32 v148, v148
	v_exp_f32_e32 v149, v149
	v_mul_f32_e32 v158, 0xbfcc422a, v158
	v_mul_f32_e32 v159, 0xbfcc422a, v159
	v_min_f32_e32 v158, 0x42a00000, v158
	v_min_f32_e32 v159, 0x42a00000, v159
	v_mul_f32_e32 v158, 0x3fb8aa3b, v158
	v_mul_f32_e32 v159, 0x3fb8aa3b, v159
	v_exp_f32_e32 v158, v158
	v_exp_f32_e32 v159, v159
	v_pk_add_f32 v[148:149], v[148:149], 1.0 op_sel_hi:[1,0]
	v_readlane_b32 s80, v244, 14
	v_rcp_f32_e32 v156, v148
	v_rcp_f32_e32 v157, v149
	v_pk_add_f32 v[158:159], v[158:159], 1.0 op_sel_hi:[1,0]
	v_readlane_b32 s92, v244, 26
	v_rcp_f32_e32 v160, v158
	v_rcp_f32_e32 v161, v159
	v_pk_fma_f32 v[148:149], v[148:149], v[156:157], 1.0 op_sel_hi:[1,1,0] neg_lo:[1,0,0] neg_hi:[1,0,0]
	v_readlane_b32 s93, v244, 27
	v_pk_fma_f32 v[148:149], v[156:157], v[148:149], v[156:157]
	v_or_b32_e32 v156, 16, v201
	v_pk_mul_f32 v[146:147], v[146:147], v[148:149]
	s_and_b64 vcc, exec, s[18:19]
	v_pk_mul_f32 v[142:143], v[142:143], v[146:147]
	v_pk_fma_f32 v[146:147], v[158:159], v[160:161], 1.0 op_sel_hi:[1,1,0] neg_lo:[1,0,0] neg_hi:[1,0,0]
	v_cvt_pk_bf16_f32 v142, v142, v143
	v_pk_fma_f32 v[146:147], v[160:161], v[146:147], v[160:161]
	v_readlane_b32 s81, v244, 15
	v_pk_mul_f32 v[146:147], v[154:155], v[146:147]
	v_readlane_b32 s82, v244, 16
	v_pk_mul_f32 v[144:145], v[144:145], v[146:147]
	v_pk_fma_f32 v[146:147], v[38:39], v[150:151], v[50:51]
	v_pk_fma_f32 v[150:151], v[40:41], v[152:153], v[52:53]
	v_pk_fma_f32 v[146:147], v[42:43], v[162:163], v[146:147]
	v_pk_fma_f32 v[150:151], v[44:45], v[164:165], v[150:151]
	v_pk_fma_f32 v[146:147], v[130:131], v[46:47], v[146:147]
	v_pk_fma_f32 v[150:151], v[132:133], v[48:49], v[150:151]
	v_mul_f32_e32 v143, 0x3d372713, v146
	v_mul_f32_e32 v143, v146, v143
	v_fma_f32 v143, v146, v143, v146
	v_mul_f32_e32 v143, 0xbfcc422a, v143
	v_min_f32_e32 v143, 0x42a00000, v143
	v_mul_f32_e32 v143, 0x3fb8aa3b, v143
	v_exp_f32_e32 v148, v143
	v_mul_f32_e32 v143, 0x3d372713, v147
	v_mul_f32_e32 v143, v147, v143
	v_fma_f32 v143, v147, v143, v147
	v_mul_f32_e32 v143, 0xbfcc422a, v143
	v_min_f32_e32 v143, 0x42a00000, v143
	v_mul_f32_e32 v143, 0x3fb8aa3b, v143
	v_exp_f32_e32 v149, v143
	v_mul_f32_e32 v143, 0x3d372713, v150
	v_mul_f32_e32 v143, v150, v143
	v_fma_f32 v143, v150, v143, v150
	v_mul_f32_e32 v143, 0xbfcc422a, v143
	v_min_f32_e32 v143, 0x42a00000, v143
	v_mul_f32_e32 v143, 0x3fb8aa3b, v143
	v_exp_f32_e32 v154, v143
	v_mul_f32_e32 v143, 0x3d372713, v151
	v_mul_f32_e32 v143, v151, v143
	v_fma_f32 v143, v151, v143, v151
	v_mul_f32_e32 v143, 0xbfcc422a, v143
	v_min_f32_e32 v143, 0x42a00000, v143
	v_pk_add_f32 v[148:149], v[148:149], 1.0 op_sel_hi:[1,0]
	v_mul_f32_e32 v143, 0x3fb8aa3b, v143
	v_rcp_f32_e32 v152, v148
	v_rcp_f32_e32 v153, v149
	v_exp_f32_e32 v155, v143
	v_cvt_pk_bf16_f32 v143, v144, v145
	v_readlane_b32 s83, v244, 17
	v_pk_fma_f32 v[144:145], v[148:149], v[152:153], 1.0 op_sel_hi:[1,1,0] neg_lo:[1,0,0] neg_hi:[1,0,0]
	v_pk_add_f32 v[148:149], v[154:155], 1.0 op_sel_hi:[1,0]
	v_pk_fma_f32 v[144:145], v[152:153], v[144:145], v[152:153]
	v_rcp_f32_e32 v154, v148
	v_rcp_f32_e32 v155, v149
	v_pk_mul_f32 v[144:145], v[146:147], v[144:145]
	v_readlane_b32 s84, v244, 18
	v_pk_mul_f32 v[138:139], v[138:139], v[144:145]
	v_pk_fma_f32 v[144:145], v[148:149], v[154:155], 1.0 op_sel_hi:[1,1,0] neg_lo:[1,0,0] neg_hi:[1,0,0]
	v_readlane_b32 s85, v244, 19
	v_pk_fma_f32 v[144:145], v[154:155], v[144:145], v[154:155]
	v_readlane_b32 s86, v244, 20
	v_pk_mul_f32 v[144:145], v[150:151], v[144:145]
	v_readlane_b32 s87, v244, 21
	v_pk_mul_f32 v[140:141], v[140:141], v[144:145]
	v_cvt_pk_bf16_f32 v144, v138, v139
	v_cvt_pk_bf16_f32 v145, v140, v141
	v_mad_i64_i32 v[138:139], s[56:57], v156, s79, v[178:179]
	global_store_dwordx4 v[138:139], v[142:145], off
	v_add_u32_e32 v138, 0xffffc020, v201
	v_ashrrev_i32_e32 v138, 2, v138
	v_ashrrev_i32_e32 v139, 31, v138
	v_mad_i64_i32 v[140:141], s[56:57], v138, s77, 0
	v_lshl_add_u64 v[138:139], v[138:139], 1, v[202:203]
	v_mad_u64_u32 v[154:155], s[56:57], v138, s78, 0
	v_lshl_add_u64 v[152:153], s[92:93], 0, v[140:141]
	v_mad_i32_i24 v155, v139, s78, v155
	s_mov_b64 s[56:57], -1
	v_lshl_add_u64 v[150:151], v[214:215], 2, v[152:153]
	v_readlane_b32 s88, v244, 22
	v_readlane_b32 s89, v244, 23
	v_readlane_b32 s90, v244, 24
	v_readlane_b32 s91, v244, 25
	v_readlane_b32 s94, v244, 28
	v_readlane_b32 s95, v244, 29
	s_cbranch_vccnz .LBB0_1007
	v_add_co_u32_e32 v142, vcc, 0x2000, v150
	v_mov_b32_e32 v156, 0
	s_nop 0
	v_addc_co_u32_e32 v143, vcc, 0, v151, vcc
	global_load_dwordx4 v[138:141], v[150:151], off
	s_nop 0
	global_load_dwordx4 v[142:145], v[142:143], off offset:3072
	v_mov_b32_e32 v157, 0
	v_mov_b32_e32 v158, 0
	v_mov_b32_e32 v159, 0
	v_mov_b32_e32 v146, 0
	v_mov_b32_e32 v147, 0
	v_mov_b32_e32 v148, 0
	v_mov_b32_e32 v149, 0
	v_mov_b32_dpp v156, v118 row_ror:1 row_mask:0xf bank_mask:0xf
	v_mov_b32_dpp v157, v119 row_ror:1 row_mask:0xf bank_mask:0xf
	v_mov_b32_dpp v158, v120 row_ror:1 row_mask:0xf bank_mask:0xf
	v_mov_b32_dpp v159, v121 row_ror:1 row_mask:0xf bank_mask:0xf
	v_mov_b32_dpp v146, v118 row_ror:2 row_mask:0xf bank_mask:0xf
	v_mov_b32_dpp v147, v119 row_ror:2 row_mask:0xf bank_mask:0xf
	v_mov_b32_dpp v148, v120 row_ror:2 row_mask:0xf bank_mask:0xf
	v_mov_b32_dpp v149, v121 row_ror:2 row_mask:0xf bank_mask:0xf
	s_waitcnt vmcnt(0)
	v_cndmask_b32_e64 v141, v141, v145, s[10:11]
	v_cndmask_b32_e64 v140, v140, v144, s[10:11]
	v_cndmask_b32_e64 v139, v139, v143, s[10:11]
	v_cndmask_b32_e64 v138, v138, v142, s[10:11]
	s_and_saveexec_b64 s[56:57], s[8:9]
	s_cbranch_execz .LBB0_1006
	v_lshl_add_u64 v[138:139], s[42:43], 0, v[154:155]
	v_lshl_add_u64 v[138:139], v[214:215], 2, v[138:139]
	global_store_dwordx4 v[138:139], v[118:121], off
	v_mov_b64_e32 v[138:139], v[146:147]
	v_mov_b64_e32 v[140:141], v[148:149]
